# attention tile loops: lane^32 exchanges via v_permlane32_swap instead of ds_bpermute+wait; lazy-softmax slow-path test flattened (20 -> 9 instr)
# speedup vs baseline: 1.0202x; 1.0202x over previous
; #define LAS __attribute__((address_space(3)))
; DI float fexp2(float x) { return __builtin_amdgcn_exp2f(x); }
; DI f32x16 mfma32(bf16x8 a, bf16x8 b, f32x16 c) { return __builtin_amdgcn_mfma_f32_32x32x16_bf16(a, b, c, 0, 0, 0); }
; DI void pv_sub(const LAS unsigned char* vt, int vstride, int koff_bytes, const f32x16& p, f32x16 (&o)[2], int r, int hh) {
;     const bf16x8 pf0 = pack8<0>(p), pf1 = pack8<1>(p);
; #pragma unroll
;     for (int st = 0; st < 2; ++st) {
;         u32x2 lo[2], hi[2];
; #pragma unroll
;         for (int u = 0; u < 2; ++u) {
;             const LAS unsigned char* a = vt + (32 * u + r) * vstride + koff_bytes + 32 * st + 8 * hh;
;             lo[u] = *(const LAS u32x2*)a; hi[u] = *(const LAS u32x2*)(a + 16);
;         }
;         __builtin_amdgcn_sched_barrier(0);
; #pragma unroll
;         for (int u = 0; u < 2; ++u) { u32x4 v; v.x = lo[u].x; v.y = lo[u].y; v.z = hi[u].x; v.w = hi[u].y; o[u] = mfma32(__builtin_bit_cast(bf16x8, v), st ? pf1 : pf0, o[u]); }
;     }
; DI void softmax_lazy(f32x16 (&s)[2], float& m, float& l, f32x16 (&o)[2], int hh) {
;     ...
;     float sum = 0.f;
; #pragma unroll
;     for (int t = 0; t < 2; ++t)
; #pragma unroll
;         for (int i = 0; i < 16; ++i) { s[t][i] = fexp2(s[t][i]); sum += s[t][i]; }
;     sum += __shfl_xor(sum, 32);
;     l += sum;
.LBB0_2419:
	v_exp_f32_e32 v0, v160
	v_exp_f32_e32 v3, v161
	v_exp_f32_e32 v7, v162
	v_exp_f32_e32 v9, v163
	v_add_f32_e32 v2, 0, v0
	v_exp_f32_e32 v10, v164
	v_add_f32_e32 v2, v3, v2
	v_exp_f32_e32 v11, v165
	v_add_f32_e32 v2, v7, v2
	v_exp_f32_e32 v12, v166
	v_add_f32_e32 v2, v9, v2
	v_exp_f32_e32 v13, v167
	v_add_f32_e32 v2, v10, v2
	v_exp_f32_e32 v14, v168
	v_add_f32_e32 v2, v11, v2
	v_exp_f32_e32 v15, v169
	v_add_f32_e32 v2, v12, v2
	v_exp_f32_e32 v160, v170
	v_add_f32_e32 v2, v13, v2
	v_exp_f32_e32 v161, v171
	v_add_f32_e32 v2, v14, v2
	v_exp_f32_e32 v162, v172
	v_add_f32_e32 v2, v15, v2
	v_exp_f32_e32 v163, v173
	v_add_f32_e32 v2, v160, v2
	v_exp_f32_e32 v164, v174
	v_add_f32_e32 v2, v161, v2
	v_exp_f32_e32 v165, v175
	v_add_f32_e32 v2, v162, v2
	v_exp_f32_e32 v166, v144
	v_add_f32_e32 v2, v163, v2
	v_exp_f32_e32 v167, v145
	v_add_f32_e32 v2, v164, v2
	v_exp_f32_e32 v168, v146
	v_add_f32_e32 v2, v165, v2
	v_exp_f32_e32 v169, v147
	v_add_f32_e32 v2, v166, v2
	v_exp_f32_e32 v170, v148
	v_add_f32_e32 v2, v167, v2
	v_exp_f32_e32 v171, v149
	v_add_f32_e32 v2, v168, v2
	v_exp_f32_e32 v172, v150
	v_add_f32_e32 v2, v169, v2
	v_exp_f32_e32 v173, v151
	v_add_f32_e32 v2, v170, v2
	v_exp_f32_e32 v152, v152
	v_add_f32_e32 v2, v171, v2
	v_exp_f32_e32 v153, v153
	v_add_f32_e32 v2, v172, v2
	v_exp_f32_e32 v154, v154
	v_add_f32_e32 v2, v173, v2
	v_exp_f32_e32 v155, v155
	v_add_f32_e32 v2, v152, v2
	v_exp_f32_e32 v156, v156
	v_add_f32_e32 v2, v153, v2
	v_exp_f32_e32 v157, v157
	v_add_f32_e32 v2, v154, v2
	v_exp_f32_e32 v158, v158
	v_add_f32_e32 v2, v155, v2
	v_exp_f32_e32 v159, v159
	v_add_f32_e32 v2, v156, v2
	v_add_f32_e32 v2, v157, v2
	v_add_f32_e32 v2, v158, v2
	v_add_f32_e32 v2, v159, v2
	v_mov_b32_e32 v8, v2
	v_cvt_pk_bf16_f32 v9, v7, v9
	v_cvt_pk_bf16_f32 v10, v10, v11
	v_cvt_pk_bf16_f32 v11, v12, v13
	v_cvt_pk_bf16_f32 v12, v14, v15
	v_permlane32_swap_b32_e32 v8, v2
	v_add_f32_e32 v2, v2, v8
	v_cvt_pk_bf16_f32 v8, v0, v3
	v_add3_u32 v0, s0, v211, v242
	v_add_f32_e32 v245, v245, v2
	v_add_u32_e32 v2, 0xa800, v0
	v_add_u32_e32 v0, 0xb800, v0
	ds_read2_b64 v[144:147], v2 offset0:192 offset1:194
	ds_read2_b64 v[148:151], v0 offset0:224 offset1:226
	v_cvt_pk_bf16_f32 v13, v160, v161
	v_cvt_pk_bf16_f32 v14, v162, v163
	v_cvt_pk_bf16_f32 v15, v164, v165
	s_waitcnt lgkmcnt(0)
	v_mfma_f32_32x32x16_bf16 v[128:143], v[144:147], v[8:11], v[128:143]
	v_mfma_f32_32x32x16_bf16 v[112:127], v[148:151], v[8:11], v[112:127]
	ds_read2_b64 v[8:11], v2 offset0:196 offset1:198
	ds_read2_b64 v[144:147], v0 offset0:228 offset1:230
	s_waitcnt lgkmcnt(0)
	v_mfma_f32_32x32x16_bf16 v[128:143], v[8:11], v[12:15], v[128:143]
	v_cvt_pk_bf16_f32 v8, v166, v167
	v_cvt_pk_bf16_f32 v9, v168, v169
	v_cvt_pk_bf16_f32 v10, v170, v171
	v_cvt_pk_bf16_f32 v11, v172, v173
	v_mfma_f32_32x32x16_bf16 v[112:127], v[144:147], v[12:15], v[112:127]
	ds_read2_b64 v[144:147], v2 offset0:200 offset1:202
	ds_read2_b64 v[148:151], v0 offset0:232 offset1:234
	v_cvt_pk_bf16_f32 v12, v152, v153
	v_cvt_pk_bf16_f32 v13, v154, v155
	v_cvt_pk_bf16_f32 v14, v156, v157
	v_cvt_pk_bf16_f32 v15, v158, v159
	s_waitcnt lgkmcnt(0)
	v_mfma_f32_32x32x16_bf16 v[128:143], v[144:147], v[8:11], v[128:143]
	v_mfma_f32_32x32x16_bf16 v[112:127], v[148:151], v[8:11], v[112:127]
	ds_read2_b64 v[8:11], v2 offset0:204 offset1:206
	ds_read2_b64 v[144:147], v0 offset0:236 offset1:238
	s_waitcnt lgkmcnt(0)
	v_mfma_f32_32x32x16_bf16 v[128:143], v[8:11], v[12:15], v[128:143]
	v_mfma_f32_32x32x16_bf16 v[112:127], v[144:147], v[12:15], v[112:127]

; DI float fexp2(float x) { return __builtin_amdgcn_exp2f(x); }
; DI f32x16 mfma32(bf16x8 a, bf16x8 b, f32x16 c) { return __builtin_amdgcn_mfma_f32_32x32x16_bf16(a, b, c, 0, 0, 0); }
; DI void softmax_lazy(f32x16 (&s)[2], float& m, float& l, f32x16 (&o)[2], int hh) {
;     float mx = s[0][0];
; #pragma unroll
;     for (int i = 1; i < 16; ++i) mx = fmaxf(mx, s[0][i]);
; #pragma unroll
;     for (int i = 0; i < 16; ++i) mx = fmaxf(mx, s[1][i]);
;     mx = fmaxf(mx, __shfl_xor(mx, 32));
;     const bool live = mx > -1e29f;
;     const bool slow = live && (mx > 32.f || (mx < -32.f && l == 0.f));
;     if (__ballot(slow) != 0ull) {
;         const float shift = (live && (mx > 0.f || l == 0.f)) ? mx : 0.f;
;         const float alpha = (l == 0.f) ? 0.f : fexp2(-shift);
;         const bf16x8 of = ones_frag(hh), sf = ref_frag(-shift, 0.f, hh);
;         s[0] = mfma32(of, sf, s[0]); s[1] = mfma32(of, sf, s[1]);
;         l *= alpha; m += shift;
;         o[0] *= alpha; o[1] *= alpha;
;     }
.LBB0_2430:
	s_or_b64 exec, exec, s[6:7]
	s_nop 2
	v_max_f32_e32 v0, v161, v161
	v_max_f32_e32 v2, v160, v160
	v_max_f32_e32 v0, v2, v0
	v_max3_f32 v0, v0, v162, v163
	v_max3_f32 v0, v0, v164, v165
	v_max3_f32 v0, v0, v166, v167
	v_max3_f32 v0, v0, v168, v169
	v_max3_f32 v0, v0, v170, v171
	v_max3_f32 v0, v0, v172, v173
	v_max3_f32 v0, v0, v174, v175
	v_max3_f32 v0, v0, v144, v145
	v_max3_f32 v0, v0, v146, v147
	v_max3_f32 v0, v0, v148, v149
	v_max3_f32 v0, v0, v150, v151
	v_max3_f32 v0, v0, v152, v153
	v_max3_f32 v0, v0, v154, v155
	v_max3_f32 v0, v0, v156, v157
	v_max3_f32 v0, v0, v158, v159
	v_mov_b32_e32 v2, v0
	s_mov_b64 s[30:31], 0
	s_nop 0
	v_permlane32_swap_b32_e32 v2, v0
	v_max_f32_e32 v2, v2, v2
	v_max_f32_e32 v0, v0, v2
	v_cmp_lt_f32_e64 s[4:5], s40, v0
	v_cmp_lt_f32_e64 s[30:31], s63, v0
	v_cmp_gt_f32_e64 s[34:35], s76, v0
	v_cmp_eq_f32_e32 vcc, 0, v245
	s_and_b64 s[34:35], s[34:35], vcc
	s_or_b64 s[30:31], s[30:31], s[34:35]
	s_and_b64 s[30:31], s[30:31], s[4:5]
	s_cmp_eq_u64 s[30:31], 0
	s_cbranch_scc1 .LBB0_2419
	v_cmp_lt_f32_e32 vcc, 0, v0
	v_cmp_eq_f32_e64 s[6:7], 0, v245
	s_or_b64 s[30:31], vcc, s[6:7]
	s_and_b64 vcc, s[4:5], s[30:31]
	v_cndmask_b32_e32 v7, 0, v0, vcc
	v_exp_f32_e64 v0, -v7
	v_mov_b32_e32 v3, v1
	v_add_f32_e32 v4, v4, v7
	v_cndmask_b32_e64 v8, v0, 0, s[6:7]
	v_cvt_pk_bf16_f32 v0, -v7, s0
	v_perm_b32 v0, 0, v0, v229
	v_lshlrev_b32_e32 v2, 16, v0
	v_sub_f32_e64 v2, -v7, v2
	v_cvt_pk_bf16_f32 v2, v2, s0
	v_lshl_or_b32 v0, v2, 16, v0
	v_cndmask_b32_e64 v0, 0, v0, s[2:3]
	v_mov_b32_e32 v2, v1
	v_mul_f32_e32 v245, v245, v8
	v_pk_mul_f32 v[142:143], v[142:143], v[8:9] op_sel_hi:[1,0]
	v_mfma_f32_32x32x16_bf16 v[160:175], v[192:195], v[0:3], v[160:175]
	v_mul_f32_e64 v140, v140, v8
	v_mul_f32_e64 v141, v141, v8
	v_mul_f32_e64 v138, v138, v8
	v_mul_f32_e64 v139, v139, v8
	v_mul_f32_e64 v136, v136, v8
	v_mul_f32_e64 v137, v137, v8
	v_pk_mul_f32 v[134:135], v[134:135], v[8:9] op_sel_hi:[1,0]
	v_pk_mul_f32 v[132:133], v[132:133], v[8:9] op_sel_hi:[1,0]
	v_pk_mul_f32 v[130:131], v[130:131], v[8:9] op_sel_hi:[1,0]
	v_pk_mul_f32 v[128:129], v[128:129], v[8:9] op_sel_hi:[1,0]
	v_mfma_f32_32x32x16_bf16 v[144:159], v[192:195], v[0:3], v[144:159]
	v_mul_f32_e64 v126, v126, v8
	v_mul_f32_e64 v127, v127, v8
	v_mul_f32_e64 v124, v124, v8
	v_mul_f32_e64 v125, v125, v8
	v_mul_f32_e64 v122, v122, v8
	v_mul_f32_e64 v123, v123, v8
	v_pk_mul_f32 v[120:121], v[120:121], v[8:9] op_sel_hi:[1,0]
	v_pk_mul_f32 v[118:119], v[118:119], v[8:9] op_sel_hi:[1,0]
	v_pk_mul_f32 v[116:117], v[116:117], v[8:9] op_sel_hi:[1,0]
	v_pk_mul_f32 v[114:115], v[114:115], v[8:9] op_sel_hi:[1,0]
	v_pk_mul_f32 v[112:113], v[112:113], v[8:9] op_sel_hi:[1,0]
	s_branch .LBB0_2419

; DI float fexp2(float x) { return __builtin_amdgcn_exp2f(x); }
; DI f32x16 mfma32(bf16x8 a, bf16x8 b, f32x16 c) { return __builtin_amdgcn_mfma_f32_32x32x16_bf16(a, b, c, 0, 0, 0); }
; DI void softmax_lazy1(f32x16& s, float& m, float& l, f32x16 (&o)[2], int hh) {
;     float mx = s[0];
; #pragma unroll
;     for (int i = 1; i < 16; ++i) mx = fmaxf(mx, s[i]);
;     mx = fmaxf(mx, __shfl_xor(mx, 32));
;     const bool live = mx > -1e29f;
;     const bool slow = live && (mx > 32.f || (mx < -32.f && l == 0.f));
;     if (__ballot(slow) != 0ull) {
;         const float shift = (live && (mx > 0.f || l == 0.f)) ? mx : 0.f;
;         const float alpha = (l == 0.f) ? 0.f : fexp2(-shift);
;         s = mfma32(ones_frag(hh), ref_frag(-shift, 0.f, hh), s);
;         l *= alpha; m += shift;
;         o[0] *= alpha; o[1] *= alpha;
;     }
;     float sum = 0.f;
; #pragma unroll
;     for (int i = 0; i < 16; ++i) { s[i] = fexp2(s[i]); sum += s[i]; }
;     sum += __shfl_xor(sum, 32);
;     l += sum;
; }
.LBB0_2827:
	v_add_f32_e32 v0, v211, v212
	v_add_f32_e32 v200, v200, v0
	v_exp_f32_e32 v0, v68
	v_exp_f32_e32 v3, v69
	v_exp_f32_e32 v211, v70
	v_exp_f32_e32 v212, v71
	v_add_f32_e32 v2, 0, v0
	v_exp_f32_e32 v213, v72
	v_add_f32_e32 v2, v3, v2
	v_exp_f32_e32 v214, v73
	v_add_f32_e32 v2, v211, v2
	v_exp_f32_e32 v215, v74
	v_add_f32_e32 v2, v212, v2
	v_exp_f32_e32 v216, v75
	v_add_f32_e32 v2, v213, v2
	v_exp_f32_e32 v76, v76
	v_add_f32_e32 v2, v214, v2
	v_exp_f32_e32 v77, v77
	v_add_f32_e32 v2, v215, v2
	v_exp_f32_e32 v78, v78
	v_add_f32_e32 v2, v216, v2
	v_exp_f32_e32 v79, v79
	v_add_f32_e32 v2, v76, v2
	v_exp_f32_e32 v80, v80
	v_add_f32_e32 v2, v77, v2
	v_exp_f32_e32 v81, v81
	v_add_f32_e32 v2, v78, v2
	v_exp_f32_e32 v82, v82
	v_add_f32_e32 v2, v79, v2
	v_exp_f32_e32 v83, v83
	v_add_f32_e32 v2, v80, v2
	v_add_f32_e32 v2, v81, v2
	v_add_f32_e32 v2, v82, v2
	v_add_f32_e32 v2, v83, v2
	v_mov_b32_e32 v68, v2
	v_cvt_pk_bf16_f32 v76, v76, v77
	v_cvt_pk_bf16_f32 v77, v78, v79
	v_cvt_pk_bf16_f32 v78, v80, v81
	v_cvt_pk_bf16_f32 v80, v0, v3
	v_permlane32_swap_b32_e32 v68, v2
	v_add_f32_e32 v2, v2, v68
	v_lshl_add_u32 v0, s48, 6, v210
	v_add_f32_e32 v196, v196, v2
	v_add_u32_e32 v2, 0x3000, v0
	v_add_u32_e32 v0, 0x4000, v0
	v_cvt_pk_bf16_f32 v72, v84, v85
	v_cvt_pk_bf16_f32 v73, v86, v87
	v_cvt_pk_bf16_f32 v74, v88, v89
	v_cvt_pk_bf16_f32 v75, v90, v91
	ds_read2_b64 v[84:87], v2 offset0:128 offset1:130
	ds_read2_b64 v[88:91], v0 offset0:160 offset1:162
	s_xor_b64 s[4:5], s[22:23], -1
	v_cvt_pk_bf16_f32 v68, v92, v93
	v_cvt_pk_bf16_f32 v69, v94, v95
	v_cvt_pk_bf16_f32 v70, v96, v97
	v_cvt_pk_bf16_f32 v71, v98, v99
	v_cvt_pk_bf16_f32 v79, v82, v83
	v_cvt_pk_bf16_f32 v81, v211, v212
	v_cvt_pk_bf16_f32 v82, v213, v214
	v_cvt_pk_bf16_f32 v83, v215, v216
	s_waitcnt lgkmcnt(0)
	v_mfma_f32_32x32x16_bf16 v[4:19], v[84:87], v[72:75], v[4:19]
	v_mfma_f32_32x32x16_bf16 v[52:67], v[84:87], v[80:83], v[52:67]
	v_mfma_f32_32x32x16_bf16 v[20:35], v[88:91], v[72:75], v[20:35]
	ds_read2_b64 v[72:75], v2 offset0:132 offset1:134
	ds_read2_b64 v[84:87], v0 offset0:164 offset1:166
	v_mfma_f32_32x32x16_bf16 v[36:51], v[88:91], v[80:83], v[36:51]
	s_waitcnt lgkmcnt(0)
	v_mfma_f32_32x32x16_bf16 v[4:19], v[72:75], v[68:71], v[4:19]
	s_mov_b32 s48, 1
	s_mov_b64 s[22:23], 0
	s_and_b64 vcc, exec, s[4:5]
	v_mfma_f32_32x32x16_bf16 v[52:67], v[72:75], v[76:79], v[52:67]
	v_mfma_f32_32x32x16_bf16 v[20:35], v[84:87], v[68:71], v[20:35]
	v_mfma_f32_32x32x16_bf16 v[36:51], v[84:87], v[76:79], v[36:51]
	s_cbranch_vccnz .LBB0_2844
.LBB0_2828:
	v_lshl_or_b32 v0, s48, 5, v194
	v_mad_u32_u24 v0, v0, s80, v206
	ds_read_b128 v[68:71], v0
	ds_read_b128 v[212:215], v0 offset:32
	ds_read_b128 v[216:219], v0 offset:64
	ds_read_b128 v[234:237], v0 offset:96
	ds_read_b128 v[238:241], v0 offset:128
	ds_read_b128 v[242:245], v0 offset:160
	s_waitcnt lgkmcnt(0)
	v_mfma_f32_32x32x16_bf16 v[84:99], v[68:71], v[100:103], 0
	v_cvt_pk_bf16_f32 v0, -v199, s0
	v_perm_b32 v0, 0, v0, v229
	v_lshlrev_b32_e32 v2, 16, v0
	v_sub_f32_e64 v2, -v199, v2
	v_cvt_pk_bf16_f32 v2, v2, s0
	v_lshl_or_b32 v0, v2, 16, v0
	v_cndmask_b32_e64 v0, 0, v0, s[2:3]
	v_mfma_f32_32x32x16_bf16 v[84:99], v[212:215], v[104:107], v[84:99]
	v_mov_b32_e32 v2, v1
	v_mov_b32_e32 v3, v1
	v_cvt_pk_bf16_f32 v211, -v201, s0
	v_perm_b32 v211, 0, v211, v229
	s_mov_b64 s[6:7], 0
	v_mfma_f32_32x32x16_bf16 v[84:99], v[216:219], v[116:119], v[84:99]
	v_mfma_f32_32x32x16_bf16 v[68:83], v[68:71], v[108:111], 0
	v_mfma_f32_32x32x16_bf16 v[84:99], v[234:237], v[120:123], v[84:99]
	v_mfma_f32_32x32x16_bf16 v[68:83], v[212:215], v[112:115], v[68:83]
	v_mfma_f32_32x32x16_bf16 v[84:99], v[238:241], v[132:135], v[84:99]
	v_mfma_f32_32x32x16_bf16 v[68:83], v[216:219], v[124:127], v[68:83]
	v_mfma_f32_32x32x16_bf16 v[84:99], v[242:245], v[136:139], v[84:99]
	v_mfma_f32_32x32x16_bf16 v[68:83], v[234:237], v[128:131], v[68:83]
	v_mfma_f32_32x32x16_bf16 v[84:99], v[172:175], v[0:3], v[84:99]
	v_lshlrev_b32_e32 v0, 16, v211
	v_sub_f32_e64 v0, -v201, v0
	v_cvt_pk_bf16_f32 v0, v0, s0
	v_lshl_or_b32 v0, v0, 16, v211
	v_cndmask_b32_e64 v0, 0, v0, s[2:3]
	s_nop 6
	v_max_f32_e32 v2, v85, v85
	v_mfma_f32_32x32x16_bf16 v[68:83], v[238:241], v[140:143], v[68:83]
	v_max_f32_e32 v3, v84, v84
	v_max_f32_e32 v2, v3, v2
	v_max3_f32 v2, v2, v86, v87
	v_max3_f32 v2, v2, v88, v89
	v_max3_f32 v2, v2, v90, v91
	v_max3_f32 v2, v2, v92, v93
	v_max3_f32 v2, v2, v94, v95
	v_mfma_f32_32x32x16_bf16 v[68:83], v[242:245], v[144:147], v[68:83]
	v_max3_f32 v2, v2, v96, v97
	v_max3_f32 v212, v2, v98, v99
	v_mov_b32_e32 v2, v1
	v_mov_b32_e32 v3, v1
	v_mov_b32_e32 v213, v212
	s_nop 0
	v_mfma_f32_32x32x16_bf16 v[68:83], v[172:175], v[0:3], v[68:83]
	v_permlane32_swap_b32_e32 v213, v212
	v_max_f32_e32 v211, v213, v213
	v_max_f32_e32 v211, v212, v211
	v_cmp_lt_f32_e64 s[4:5], s40, v211
	v_cmp_lt_f32_e64 s[6:7], s63, v211
	v_cmp_gt_f32_e64 s[26:27], s76, v211
	v_cmp_eq_f32_e32 vcc, 0, v200
	s_and_b64 s[26:27], s[26:27], vcc
	s_or_b64 s[6:7], s[6:7], s[26:27]
	s_and_b64 s[6:7], s[6:7], s[4:5]
	s_cmp_eq_u64 s[6:7], 0
	s_cbranch_scc1 .LBB0_2836
	v_cmp_lt_f32_e32 vcc, 0, v211
	v_cmp_eq_f32_e64 s[6:7], 0, v200
	s_or_b64 s[24:25], vcc, s[6:7]
	s_and_b64 vcc, s[4:5], s[24:25]
	v_cndmask_b32_e32 v211, 0, v211, vcc
	v_exp_f32_e64 v0, -v211
	v_cvt_pk_bf16_f32 v2, -v211, s0
	v_mov_b32_e32 v3, v1
	v_add_f32_e32 v199, v199, v211
	v_cndmask_b32_e64 v212, v0, 0, s[6:7]
	v_perm_b32 v0, 0, v2, v229
	v_lshlrev_b32_e32 v2, 16, v0
	v_sub_f32_e64 v2, -v211, v2
	v_cvt_pk_bf16_f32 v2, v2, s0
	v_lshl_or_b32 v0, v2, 16, v0
	v_cndmask_b32_e64 v0, 0, v0, s[2:3]
	v_mov_b32_e32 v2, v1
	v_mul_f32_e32 v200, v200, v212
	v_pk_mul_f32 v[34:35], v[34:35], v[212:213] op_sel_hi:[1,0]
	v_mfma_f32_32x32x16_bf16 v[84:99], v[172:175], v[0:3], v[84:99]
	v_mul_f32_e64 v32, v32, v212
	v_mul_f32_e64 v33, v33, v212
	v_mul_f32_e64 v30, v30, v212
	v_mul_f32_e64 v31, v31, v212
	v_mul_f32_e64 v28, v28, v212
	v_mul_f32_e64 v29, v29, v212
	v_pk_mul_f32 v[26:27], v[26:27], v[212:213] op_sel_hi:[1,0]
	v_pk_mul_f32 v[24:25], v[24:25], v[212:213] op_sel_hi:[1,0]
	v_pk_mul_f32 v[22:23], v[22:23], v[212:213] op_sel_hi:[1,0]
	v_pk_mul_f32 v[20:21], v[20:21], v[212:213] op_sel_hi:[1,0]
	v_pk_mul_f32 v[18:19], v[18:19], v[212:213] op_sel_hi:[1,0]
	v_pk_mul_f32 v[16:17], v[16:17], v[212:213] op_sel_hi:[1,0]
	v_pk_mul_f32 v[14:15], v[14:15], v[212:213] op_sel_hi:[1,0]
	v_pk_mul_f32 v[12:13], v[12:13], v[212:213] op_sel_hi:[1,0]
	v_pk_mul_f32 v[10:11], v[10:11], v[212:213] op_sel_hi:[1,0]
	v_pk_mul_f32 v[8:9], v[8:9], v[212:213] op_sel_hi:[1,0]
	v_pk_mul_f32 v[6:7], v[6:7], v[212:213] op_sel_hi:[1,0]
	v_pk_mul_f32 v[4:5], v[4:5], v[212:213] op_sel_hi:[1,0]
; DI float fexp2(float x) { return __builtin_amdgcn_exp2f(x); }
; DI f32x16 mfma32(bf16x8 a, bf16x8 b, f32x16 c) { return __builtin_amdgcn_mfma_f32_32x32x16_bf16(a, b, c, 0, 0, 0); }
; DI void softmax_lazy1(f32x16& s, float& m, float& l, f32x16 (&o)[2], int hh) {
;     float mx = s[0];
; #pragma unroll
;     for (int i = 1; i < 16; ++i) mx = fmaxf(mx, s[i]);
;     mx = fmaxf(mx, __shfl_xor(mx, 32));
;     const bool live = mx > -1e29f;
;     const bool slow = live && (mx > 32.f || (mx < -32.f && l == 0.f));
;     if (__ballot(slow) != 0ull) {
;         const float shift = (live && (mx > 0.f || l == 0.f)) ? mx : 0.f;
;         const float alpha = (l == 0.f) ? 0.f : fexp2(-shift);
;         s = mfma32(ones_frag(hh), ref_frag(-shift, 0.f, hh), s);
;         l *= alpha; m += shift;
;         o[0] *= alpha; o[1] *= alpha;
;     }
;     float sum = 0.f;
; #pragma unroll
;     for (int i = 0; i < 16; ++i) { s[i] = fexp2(s[i]); sum += s[i]; }
;     sum += __shfl_xor(sum, 32);
;     l += sum;
; }
.LBB0_2836:
	v_exp_f32_e32 v84, v84
	v_exp_f32_e32 v85, v85
	v_exp_f32_e32 v86, v86
	v_exp_f32_e32 v87, v87
	v_add_f32_e32 v0, 0, v84
	v_exp_f32_e32 v88, v88
	v_add_f32_e32 v0, v85, v0
	v_exp_f32_e32 v89, v89
	v_add_f32_e32 v0, v86, v0
	v_exp_f32_e32 v90, v90
	v_add_f32_e32 v0, v87, v0
	v_exp_f32_e32 v91, v91
	v_add_f32_e32 v0, v88, v0
	v_exp_f32_e32 v92, v92
	v_max_f32_e32 v2, v69, v69
	v_max_f32_e32 v3, v68, v68
	v_add_f32_e32 v0, v89, v0
	v_exp_f32_e32 v93, v93
	v_max_f32_e32 v2, v3, v2
	v_add_f32_e32 v0, v90, v0
	v_exp_f32_e32 v94, v94
	v_max3_f32 v2, v2, v70, v71
	v_add_f32_e32 v0, v91, v0
	v_exp_f32_e32 v95, v95
	v_max3_f32 v2, v2, v72, v73
	v_add_f32_e32 v0, v92, v0
	v_exp_f32_e32 v96, v96
	v_max3_f32 v2, v2, v74, v75
	v_add_f32_e32 v0, v93, v0
	v_exp_f32_e32 v97, v97
	v_max3_f32 v2, v2, v76, v77
	v_add_f32_e32 v0, v94, v0
	v_exp_f32_e32 v98, v98
	v_max3_f32 v2, v2, v78, v79
	v_add_f32_e32 v0, v95, v0
	v_exp_f32_e32 v99, v99
	v_max3_f32 v2, v2, v80, v81
	v_add_f32_e32 v0, v96, v0
	v_max3_f32 v2, v2, v82, v83
	v_mov_b32_e32 v3, v2
	v_add_f32_e32 v0, v97, v0
	v_add_f32_e32 v0, v98, v0
	v_add_f32_e32 v211, v99, v0
	v_mov_b32_e32 v212, v211
	v_permlane32_swap_b32_e32 v3, v2
	s_nop 0
	v_permlane32_swap_b32_e32 v212, v211
	v_max_f32_e32 v0, v3, v3
	v_max_f32_e32 v0, v2, v0
	v_cmp_lt_f32_e64 s[4:5], s40, v0
	v_cmp_lt_f32_e64 s[24:25], s63, v0
	v_cmp_gt_f32_e64 s[26:27], s76, v0
	v_cmp_eq_f32_e32 vcc, 0, v196
	s_and_b64 s[26:27], s[26:27], vcc
	s_or_b64 s[24:25], s[24:25], s[26:27]
	s_and_b64 s[24:25], s[24:25], s[4:5]
	s_cmp_eq_u64 s[24:25], 0
	s_cbranch_scc1 .LBB0_2827
	v_cmp_lt_f32_e32 vcc, 0, v0
	v_cmp_eq_f32_e64 s[6:7], 0, v196
	s_or_b64 s[24:25], vcc, s[6:7]
	s_and_b64 vcc, s[4:5], s[24:25]
	v_cndmask_b32_e32 v213, 0, v0, vcc
	v_exp_f32_e64 v0, -v213
	v_cvt_pk_bf16_f32 v2, -v213, s0
	v_mov_b32_e32 v3, v1
	v_add_f32_e32 v201, v201, v213
	v_cndmask_b32_e64 v214, v0, 0, s[6:7]
	v_perm_b32 v0, 0, v2, v229
	v_lshlrev_b32_e32 v2, 16, v0
	v_sub_f32_e64 v2, -v213, v2
	v_cvt_pk_bf16_f32 v2, v2, s0
	v_lshl_or_b32 v0, v2, 16, v0
	v_cndmask_b32_e64 v0, 0, v0, s[2:3]
	v_mov_b32_e32 v2, v1
	v_mul_f32_e32 v196, v196, v214
	v_pk_mul_f32 v[66:67], v[66:67], v[214:215] op_sel_hi:[1,0]
	v_mfma_f32_32x32x16_bf16 v[68:83], v[172:175], v[0:3], v[68:83]
	v_mul_f32_e64 v64, v64, v214
	v_mul_f32_e64 v65, v65, v214
	v_mul_f32_e64 v62, v62, v214
	v_mul_f32_e64 v63, v63, v214
	v_mul_f32_e64 v60, v60, v214
	v_mul_f32_e64 v61, v61, v214
	v_pk_mul_f32 v[58:59], v[58:59], v[214:215] op_sel_hi:[1,0]
	v_pk_mul_f32 v[56:57], v[56:57], v[214:215] op_sel_hi:[1,0]
	v_pk_mul_f32 v[54:55], v[54:55], v[214:215] op_sel_hi:[1,0]
	v_pk_mul_f32 v[52:53], v[52:53], v[214:215] op_sel_hi:[1,0]
	v_pk_mul_f32 v[50:51], v[50:51], v[214:215] op_sel_hi:[1,0]
	v_pk_mul_f32 v[48:49], v[48:49], v[214:215] op_sel_hi:[1,0]
	v_pk_mul_f32 v[46:47], v[46:47], v[214:215] op_sel_hi:[1,0]
	v_pk_mul_f32 v[44:45], v[44:45], v[214:215] op_sel_hi:[1,0]
	v_pk_mul_f32 v[42:43], v[42:43], v[214:215] op_sel_hi:[1,0]
	v_pk_mul_f32 v[40:41], v[40:41], v[214:215] op_sel_hi:[1,0]
	v_pk_mul_f32 v[38:39], v[38:39], v[214:215] op_sel_hi:[1,0]
	v_pk_mul_f32 v[36:37], v[36:37], v[214:215] op_sel_hi:[1,0]
	s_branch .LBB0_2827

; DI float fexp2(float x) { return __builtin_amdgcn_exp2f(x); }
; DI f32x16 mfma32(bf16x8 a, bf16x8 b, f32x16 c) { return __builtin_amdgcn_mfma_f32_32x32x16_bf16(a, b, c, 0, 0, 0); }
; DI int crow(int i, int hh) { return (i & 3) + 8 * (i >> 2) + 4 * hh; }
; DI void softmax_lazy1(f32x16& s, float& m, float& l, f32x16 (&o)[2], int hh) {
;     float mx = s[0];
; #pragma unroll
;     for (int i = 1; i < 16; ++i) mx = fmaxf(mx, s[i]);
;     mx = fmaxf(mx, __shfl_xor(mx, 32));
;     const bool live = mx > -1e29f;
;     const bool slow = live && (mx > 32.f || (mx < -32.f && l == 0.f));
;     if (__ballot(slow) != 0ull) {
;         const float shift = (live && (mx > 0.f || l == 0.f)) ? mx : 0.f;
;         const float alpha = (l == 0.f) ? 0.f : fexp2(-shift);
;         s = mfma32(ones_frag(hh), ref_frag(-shift, 0.f, hh), s);
;         l *= alpha; m += shift;
;         o[0] *= alpha; o[1] *= alpha;
;     }
;     float sum = 0.f;
; #pragma unroll
;     for (int i = 0; i < 16; ++i) { s[i] = fexp2(s[i]); sum += s[i]; }
;     sum += __shfl_xor(sum, 32);
;     l += sum;
; }
; DI void mla_qblock(int wv, int w, LAS unsigned char* lds, const bf16_t* Q, const bf16_t* KN, const bf16_t* KR, const bf16_t* VT, bf16_t* O, size_t tok0, int h, int qb) {
;     ...
;             for (int tt = 0; tt < 2; ++tt) {
;                 f32x16 s0, s1;
;                 MLA_QK1(tt);
; #pragma unroll
;                 for (int i = 0; i < 16; ++i) { const int key = k0 + 32 * tt + crow(i, hh); if (key > tq0) s0[i] = NEGF; if (key > tq1) s1[i] = NEGF; }
;                 softmax_lazy1(s0, m0, l0, o0, hh); softmax_lazy1(s1, m1, l1, o1, hh);
;                 pv_sub2(kb + VOFF, VS, 64 * tt, s0, s1, o0, o1, r, hh);
.LBB0_2859:
	v_add_f32_e32 v0, v169, v170
	v_add_f32_e32 v200, v200, v0
	v_exp_f32_e32 v0, v84
	v_exp_f32_e32 v3, v85
	v_exp_f32_e32 v84, v86
	v_exp_f32_e32 v85, v87
	v_add_f32_e32 v2, 0, v0
	v_exp_f32_e32 v86, v88
	v_add_f32_e32 v2, v3, v2
	v_exp_f32_e32 v87, v89
	v_add_f32_e32 v2, v84, v2
	v_exp_f32_e32 v88, v90
	v_add_f32_e32 v2, v85, v2
	v_exp_f32_e32 v89, v91
	v_add_f32_e32 v2, v86, v2
	v_exp_f32_e32 v90, v92
	v_add_f32_e32 v2, v87, v2
	v_exp_f32_e32 v91, v93
	v_add_f32_e32 v2, v88, v2
	v_exp_f32_e32 v92, v94
	v_add_f32_e32 v2, v89, v2
	v_exp_f32_e32 v93, v95
	v_add_f32_e32 v2, v90, v2
	v_exp_f32_e32 v94, v96
	v_add_f32_e32 v2, v91, v2
	v_exp_f32_e32 v95, v97
	v_add_f32_e32 v2, v92, v2
	v_exp_f32_e32 v96, v98
	v_add_f32_e32 v2, v93, v2
	v_exp_f32_e32 v97, v99
	v_add_f32_e32 v2, v94, v2
	v_add_f32_e32 v2, v95, v2
	v_add_f32_e32 v2, v96, v2
	v_add_f32_e32 v2, v97, v2
	v_mov_b32_e32 v98, v2
	v_cvt_pk_bf16_f32 v76, v76, v77
	v_cvt_pk_bf16_f32 v77, v78, v79
	v_cvt_pk_bf16_f32 v78, v80, v81
	v_cvt_pk_bf16_f32 v80, v0, v3
	v_permlane32_swap_b32_e32 v98, v2
	v_add_f32_e32 v2, v2, v98
	v_add_f32_e32 v196, v196, v2
	v_lshl_add_u32 v2, s46, 6, v167
	v_add_u32_e32 v0, v2, v197
	v_add_u32_e32 v2, v2, v198
	v_add_u32_e32 v0, 0x3000, v0
	v_add_u32_e32 v2, 0x3000, v2
	v_cvt_pk_bf16_f32 v79, v82, v83
	v_cvt_pk_bf16_f32 v68, v68, v69
	v_cvt_pk_bf16_f32 v69, v70, v71
	v_cvt_pk_bf16_f32 v70, v72, v73
	v_cvt_pk_bf16_f32 v72, v90, v91
	v_cvt_pk_bf16_f32 v81, v84, v85
	v_cvt_pk_bf16_f32 v82, v86, v87
	v_cvt_pk_bf16_f32 v83, v88, v89
	ds_read2_b64 v[84:87], v0 offset0:128 offset1:130
	ds_read2_b64 v[88:91], v2 offset0:128 offset1:130
	s_xor_b64 s[4:5], s[22:23], -1
	v_cvt_pk_bf16_f32 v71, v74, v75
	v_cvt_pk_bf16_f32 v73, v92, v93
	v_cvt_pk_bf16_f32 v74, v94, v95
	v_cvt_pk_bf16_f32 v75, v96, v97
	s_waitcnt lgkmcnt(0)
	v_mfma_f32_32x32x16_bf16 v[4:19], v[84:87], v[68:71], v[4:19]
	v_mfma_f32_32x32x16_bf16 v[52:67], v[84:87], v[80:83], v[52:67]
	v_mfma_f32_32x32x16_bf16 v[20:35], v[88:91], v[68:71], v[20:35]
	ds_read2_b64 v[68:71], v0 offset0:132 offset1:134
	ds_read2_b64 v[84:87], v2 offset0:132 offset1:134
	v_mfma_f32_32x32x16_bf16 v[36:51], v[88:91], v[80:83], v[36:51]
	s_waitcnt lgkmcnt(0)
	v_mfma_f32_32x32x16_bf16 v[4:19], v[68:71], v[76:79], v[4:19]
	s_mov_b32 s46, 1
	s_mov_b64 s[22:23], 0
	s_andn2_b64 vcc, exec, s[4:5]
	v_mfma_f32_32x32x16_bf16 v[52:67], v[68:71], v[72:75], v[52:67]
	v_mfma_f32_32x32x16_bf16 v[20:35], v[84:87], v[76:79], v[20:35]
	v_mfma_f32_32x32x16_bf16 v[36:51], v[84:87], v[72:75], v[36:51]
	s_cbranch_vccz .LBB0_2876
.LBB0_2860:
	s_lshl_b32 s4, s46, 5
	v_or_b32_e32 v0, s4, v194
	v_mad_u32_u24 v0, v0, s80, v165
	ds_read_b128 v[84:87], v0
	ds_read_b128 v[170:173], v0 offset:32
	ds_read_b128 v[202:205], v0 offset:64
	ds_read_b128 v[210:213], v0 offset:96
	ds_read_b128 v[214:217], v0 offset:128
	ds_read_b128 v[218:221], v0 offset:160
	s_waitcnt lgkmcnt(0)
	v_mfma_f32_32x32x16_bf16 v[68:83], v[84:87], v[100:103], 0
	v_cvt_pk_bf16_f32 v0, -v199, s0
	v_perm_b32 v0, 0, v0, v229
	v_lshlrev_b32_e32 v2, 16, v0
	v_sub_f32_e64 v2, -v199, v2
	v_cvt_pk_bf16_f32 v2, v2, s0
	v_lshl_or_b32 v0, v2, 16, v0
	v_cndmask_b32_e64 v0, 0, v0, s[2:3]
	v_mfma_f32_32x32x16_bf16 v[68:83], v[170:173], v[104:107], v[68:83]
	v_mov_b32_e32 v2, v1
	v_mov_b32_e32 v3, v1
	v_or_b32_e32 v169, s4, v168
	v_cmp_le_i32_e32 vcc, v169, v178
	v_or_b32_e32 v174, 10, v169
	v_or_b32_e32 v175, 11, v169
	v_cmp_lt_i32_e64 s[4:5], v169, v178
	v_mfma_f32_32x32x16_bf16 v[84:99], v[84:87], v[108:111], 0
	v_or_b32_e32 v206, 24, v169
	s_mov_b64 s[24:25], 0
	v_mfma_f32_32x32x16_bf16 v[68:83], v[202:205], v[116:119], v[68:83]
	v_mfma_f32_32x32x16_bf16 v[84:99], v[170:173], v[112:115], v[84:99]
	v_or_b32_e32 v170, 2, v169
	v_or_b32_e32 v171, 3, v169
	v_or_b32_e32 v172, 8, v169
	v_or_b32_e32 v173, 9, v169
	v_mfma_f32_32x32x16_bf16 v[68:83], v[210:213], v[120:123], v[68:83]
	v_mfma_f32_32x32x16_bf16 v[84:99], v[202:205], v[124:127], v[84:99]
	v_or_b32_e32 v202, 16, v169
	v_or_b32_e32 v203, 17, v169
	v_or_b32_e32 v204, 18, v169
	v_or_b32_e32 v205, 19, v169
	v_mfma_f32_32x32x16_bf16 v[68:83], v[214:217], v[132:135], v[68:83]
	v_mfma_f32_32x32x16_bf16 v[84:99], v[210:213], v[128:131], v[84:99]
	v_or_b32_e32 v210, 25, v169
	v_or_b32_e32 v211, 26, v169
	v_or_b32_e32 v212, 27, v169
	v_mfma_f32_32x32x16_bf16 v[68:83], v[218:221], v[136:139], v[68:83]
	v_mfma_f32_32x32x16_bf16 v[84:99], v[214:217], v[140:143], v[84:99]
	v_mfma_f32_32x32x16_bf16 v[68:83], v[160:163], v[0:3], v[68:83]
	v_cvt_pk_bf16_f32 v0, -v201, s0
	v_perm_b32 v0, 0, v0, v229
	v_lshlrev_b32_e32 v2, 16, v0
	v_sub_f32_e64 v2, -v201, v2
	v_cvt_pk_bf16_f32 v2, v2, s0
	v_lshl_or_b32 v0, v2, 16, v0
	v_cndmask_b32_e64 v0, 0, v0, s[2:3]
	v_mfma_f32_32x32x16_bf16 v[84:99], v[218:221], v[144:147], v[84:99]
	s_nop 3
	v_cndmask_b32_e32 v68, v231, v68, vcc
	v_cmp_le_i32_e32 vcc, v170, v178
	v_mov_b32_e32 v2, v1
	v_cndmask_b32_e64 v69, v231, v69, s[4:5]
	v_cndmask_b32_e32 v70, v231, v70, vcc
	v_cmp_le_i32_e32 vcc, v171, v178
	v_mfma_f32_32x32x16_bf16 v[84:99], v[160:163], v[0:3], v[84:99]
	s_nop 0
	v_cndmask_b32_e32 v71, v231, v71, vcc
	v_cmp_le_i32_e32 vcc, v172, v178
	v_max_f32_e32 v0, v69, v69
	v_max_f32_e32 v2, v68, v68
	v_cndmask_b32_e32 v72, v231, v72, vcc
	v_cmp_le_i32_e32 vcc, v173, v178
	v_max_f32_e32 v0, v2, v0
	v_max3_f32 v0, v0, v70, v71
	v_cndmask_b32_e32 v73, v231, v73, vcc
	v_cmp_le_i32_e32 vcc, v174, v178
	v_max3_f32 v0, v0, v72, v73
	s_nop 0
	v_cndmask_b32_e32 v74, v231, v74, vcc
	v_cmp_le_i32_e32 vcc, v175, v178
	s_nop 1
	v_cndmask_b32_e32 v75, v231, v75, vcc
	v_cmp_le_i32_e32 vcc, v202, v178
	v_max3_f32 v0, v0, v74, v75
	s_nop 0
	v_cndmask_b32_e32 v76, v231, v76, vcc
	v_cmp_le_i32_e32 vcc, v203, v178
	s_nop 1
	v_cndmask_b32_e32 v77, v231, v77, vcc
	v_cmp_le_i32_e32 vcc, v204, v178
	v_max3_f32 v0, v0, v76, v77
	s_nop 0
	v_cndmask_b32_e32 v78, v231, v78, vcc
	v_cmp_le_i32_e32 vcc, v205, v178
	s_nop 1
	v_cndmask_b32_e32 v79, v231, v79, vcc
	v_cmp_le_i32_e32 vcc, v206, v178
	v_max3_f32 v0, v0, v78, v79
	s_nop 0
	v_cndmask_b32_e32 v80, v231, v80, vcc
	v_cmp_le_i32_e32 vcc, v210, v178
	s_nop 1
	v_cndmask_b32_e32 v81, v231, v81, vcc
	v_cmp_le_i32_e32 vcc, v211, v178
	v_max3_f32 v0, v0, v80, v81
	s_nop 0
	v_cndmask_b32_e32 v82, v231, v82, vcc
	v_cmp_le_i32_e32 vcc, v212, v178
	s_nop 1
	v_cndmask_b32_e32 v83, v231, v83, vcc
	v_max3_f32 v0, v0, v82, v83
	v_mov_b32_e32 v2, v0
	s_nop 1
	v_permlane32_swap_b32_e32 v2, v0
	v_max_f32_e32 v2, v2, v2
	v_max_f32_e32 v0, v0, v2
	v_cmp_lt_f32_e64 s[4:5], s40, v0
	v_cmp_lt_f32_e64 s[24:25], s63, v0
	v_cmp_gt_f32_e64 s[26:27], s76, v0
	v_cmp_eq_f32_e32 vcc, 0, v200
	s_and_b64 s[26:27], s[26:27], vcc
	s_or_b64 s[24:25], s[24:25], s[26:27]
	s_and_b64 s[24:25], s[24:25], s[4:5]
	s_cmp_eq_u64 s[24:25], 0
	s_cbranch_scc1 .LBB0_2868
; DI float fexp2(float x) { return __builtin_amdgcn_exp2f(x); }
; DI f32x16 mfma32(bf16x8 a, bf16x8 b, f32x16 c) { return __builtin_amdgcn_mfma_f32_32x32x16_bf16(a, b, c, 0, 0, 0); }
; DI int crow(int i, int hh) { return (i & 3) + 8 * (i >> 2) + 4 * hh; }
; DI void softmax_lazy1(f32x16& s, float& m, float& l, f32x16 (&o)[2], int hh) {
;     float mx = s[0];
; #pragma unroll
;     for (int i = 1; i < 16; ++i) mx = fmaxf(mx, s[i]);
;     mx = fmaxf(mx, __shfl_xor(mx, 32));
;     const bool live = mx > -1e29f;
;     const bool slow = live && (mx > 32.f || (mx < -32.f && l == 0.f));
;     if (__ballot(slow) != 0ull) {
;         const float shift = (live && (mx > 0.f || l == 0.f)) ? mx : 0.f;
;         const float alpha = (l == 0.f) ? 0.f : fexp2(-shift);
;         s = mfma32(ones_frag(hh), ref_frag(-shift, 0.f, hh), s);
;         l *= alpha; m += shift;
;         o[0] *= alpha; o[1] *= alpha;
;     }
;     float sum = 0.f;
; #pragma unroll
;     for (int i = 0; i < 16; ++i) { s[i] = fexp2(s[i]); sum += s[i]; }
;     sum += __shfl_xor(sum, 32);
;     l += sum;
; }
; DI void mla_qblock(int wv, int w, LAS unsigned char* lds, const bf16_t* Q, const bf16_t* KN, const bf16_t* KR, const bf16_t* VT, bf16_t* O, size_t tok0, int h, int qb) {
;     ...
;                 for (int i = 0; i < 16; ++i) { const int key = k0 + 32 * tt + crow(i, hh); if (key > tq0) s0[i] = NEGF; if (key > tq1) s1[i] = NEGF; }
	v_cmp_lt_f32_e32 vcc, 0, v0
	v_cmp_eq_f32_e64 s[6:7], 0, v200
	s_or_b64 s[24:25], vcc, s[6:7]
	s_and_b64 vcc, s[4:5], s[24:25]
	v_cndmask_b32_e32 v213, 0, v0, vcc
	v_exp_f32_e64 v0, -v213
	v_cvt_pk_bf16_f32 v2, -v213, s0
	v_mov_b32_e32 v3, v1
	v_add_f32_e32 v199, v199, v213
	v_cndmask_b32_e64 v214, v0, 0, s[6:7]
	v_perm_b32 v0, 0, v2, v229
	v_lshlrev_b32_e32 v2, 16, v0
	v_sub_f32_e64 v2, -v213, v2
	v_cvt_pk_bf16_f32 v2, v2, s0
	v_lshl_or_b32 v0, v2, 16, v0
	v_cndmask_b32_e64 v0, 0, v0, s[2:3]
	v_mov_b32_e32 v2, v1
	v_mul_f32_e32 v200, v200, v214
	v_pk_mul_f32 v[34:35], v[34:35], v[214:215] op_sel_hi:[1,0]
	v_mfma_f32_32x32x16_bf16 v[68:83], v[160:163], v[0:3], v[68:83]
	v_mul_f32_e64 v32, v32, v214
	v_mul_f32_e64 v33, v33, v214
	v_mul_f32_e64 v30, v30, v214
	v_mul_f32_e64 v31, v31, v214
	v_mul_f32_e64 v28, v28, v214
	v_mul_f32_e64 v29, v29, v214
	v_pk_mul_f32 v[26:27], v[26:27], v[214:215] op_sel_hi:[1,0]
	v_pk_mul_f32 v[24:25], v[24:25], v[214:215] op_sel_hi:[1,0]
	v_pk_mul_f32 v[22:23], v[22:23], v[214:215] op_sel_hi:[1,0]
	v_pk_mul_f32 v[20:21], v[20:21], v[214:215] op_sel_hi:[1,0]
	v_pk_mul_f32 v[18:19], v[18:19], v[214:215] op_sel_hi:[1,0]
	v_pk_mul_f32 v[16:17], v[16:17], v[214:215] op_sel_hi:[1,0]
	v_pk_mul_f32 v[14:15], v[14:15], v[214:215] op_sel_hi:[1,0]
	v_pk_mul_f32 v[12:13], v[12:13], v[214:215] op_sel_hi:[1,0]
	v_pk_mul_f32 v[10:11], v[10:11], v[214:215] op_sel_hi:[1,0]
	v_pk_mul_f32 v[8:9], v[8:9], v[214:215] op_sel_hi:[1,0]
	v_pk_mul_f32 v[6:7], v[6:7], v[214:215] op_sel_hi:[1,0]
	v_pk_mul_f32 v[4:5], v[4:5], v[214:215] op_sel_hi:[1,0]
.LBB0_2868:
	v_exp_f32_e32 v68, v68
	v_exp_f32_e32 v69, v69
	v_exp_f32_e32 v70, v70
	v_exp_f32_e32 v71, v71
	v_add_f32_e32 v0, 0, v68
	v_exp_f32_e32 v72, v72
	v_add_f32_e32 v0, v69, v0
	v_exp_f32_e32 v73, v73
	v_add_f32_e32 v0, v70, v0
	v_exp_f32_e32 v74, v74
	v_add_f32_e32 v0, v71, v0
	v_exp_f32_e32 v75, v75
	v_add_f32_e32 v0, v72, v0
	v_exp_f32_e32 v76, v76
	v_add_f32_e32 v0, v73, v0
	v_exp_f32_e32 v77, v77
	v_add_f32_e32 v0, v74, v0
	v_exp_f32_e32 v78, v78
	v_cmp_le_i32_e32 vcc, v169, v180
	v_add_f32_e32 v0, v75, v0
	v_exp_f32_e32 v79, v79
	v_cndmask_b32_e32 v84, v231, v84, vcc
	v_cmp_le_i32_e32 vcc, v170, v180
	v_add_f32_e32 v0, v76, v0
	v_exp_f32_e32 v80, v80
	v_cndmask_b32_e32 v86, v231, v86, vcc
	v_cmp_le_i32_e32 vcc, v171, v180
	v_add_f32_e32 v0, v77, v0
	v_exp_f32_e32 v81, v81
	v_cndmask_b32_e32 v87, v231, v87, vcc
	v_cmp_le_i32_e32 vcc, v172, v180
	v_add_f32_e32 v0, v78, v0
	v_exp_f32_e32 v82, v82
	v_cndmask_b32_e32 v88, v231, v88, vcc
	v_cmp_le_i32_e32 vcc, v173, v180
	v_add_f32_e32 v0, v79, v0
	v_exp_f32_e32 v83, v83
	v_cndmask_b32_e32 v89, v231, v89, vcc
	v_cmp_le_i32_e32 vcc, v174, v180
	v_add_f32_e32 v0, v80, v0
	v_cmp_lt_i32_e64 s[4:5], v169, v180
	v_cndmask_b32_e32 v90, v231, v90, vcc
	v_cmp_le_i32_e32 vcc, v175, v180
	v_add_f32_e32 v0, v81, v0
	v_cndmask_b32_e64 v85, v231, v85, s[4:5]
	v_cndmask_b32_e32 v91, v231, v91, vcc
	v_cmp_le_i32_e32 vcc, v202, v180
	v_add_f32_e32 v0, v82, v0
	v_add_f32_e32 v169, v83, v0
	v_cndmask_b32_e32 v92, v231, v92, vcc
	v_cmp_le_i32_e32 vcc, v203, v180
	v_max_f32_e32 v0, v85, v85
	v_max_f32_e32 v2, v84, v84
	v_cndmask_b32_e32 v93, v231, v93, vcc
	v_cmp_le_i32_e32 vcc, v204, v180
	v_max_f32_e32 v0, v2, v0
	v_max3_f32 v0, v0, v86, v87
	v_cndmask_b32_e32 v94, v231, v94, vcc
	v_cmp_le_i32_e32 vcc, v205, v180
	v_max3_f32 v0, v0, v88, v89
	v_max3_f32 v0, v0, v90, v91
	v_cndmask_b32_e32 v95, v231, v95, vcc
	v_cmp_le_i32_e32 vcc, v206, v180
	v_max3_f32 v0, v0, v92, v93
	v_max3_f32 v0, v0, v94, v95
	v_cndmask_b32_e32 v96, v231, v96, vcc
	v_cmp_le_i32_e32 vcc, v210, v180
	v_mov_b32_e32 v170, v169
	s_mov_b64 s[24:25], 0
	v_cndmask_b32_e32 v97, v231, v97, vcc
	v_cmp_le_i32_e32 vcc, v211, v180
	v_max3_f32 v0, v0, v96, v97
	v_permlane32_swap_b32_e32 v170, v169
	v_cndmask_b32_e32 v98, v231, v98, vcc
	v_cmp_le_i32_e32 vcc, v212, v180
	s_nop 1
	v_cndmask_b32_e32 v99, v231, v99, vcc
	v_max3_f32 v0, v0, v98, v99
	v_mov_b32_e32 v2, v0
	s_nop 1
	v_permlane32_swap_b32_e32 v2, v0
	v_max_f32_e32 v2, v2, v2
	v_max_f32_e32 v0, v0, v2
	v_cmp_lt_f32_e64 s[4:5], s40, v0
	v_cmp_lt_f32_e64 s[24:25], s63, v0
	v_cmp_gt_f32_e64 s[26:27], s76, v0
	v_cmp_eq_f32_e32 vcc, 0, v196
	s_and_b64 s[26:27], s[26:27], vcc
	s_or_b64 s[24:25], s[24:25], s[26:27]
	s_and_b64 s[24:25], s[24:25], s[4:5]
	s_cmp_eq_u64 s[24:25], 0
	s_cbranch_scc1 .LBB0_2859
	v_cmp_lt_f32_e32 vcc, 0, v0
	v_cmp_eq_f32_e64 s[6:7], 0, v196
	s_or_b64 s[24:25], vcc, s[6:7]
	s_and_b64 vcc, s[4:5], s[24:25]
	v_cndmask_b32_e32 v171, 0, v0, vcc
	v_exp_f32_e64 v0, -v171
	v_cvt_pk_bf16_f32 v2, -v171, s0
	v_mov_b32_e32 v3, v1
	v_add_f32_e32 v201, v201, v171
	v_cndmask_b32_e64 v172, v0, 0, s[6:7]
	v_perm_b32 v0, 0, v2, v229
	v_lshlrev_b32_e32 v2, 16, v0
	v_sub_f32_e64 v2, -v171, v2
	v_cvt_pk_bf16_f32 v2, v2, s0
	v_lshl_or_b32 v0, v2, 16, v0
	v_cndmask_b32_e64 v0, 0, v0, s[2:3]
	v_mov_b32_e32 v2, v1
	v_mul_f32_e32 v196, v196, v172
	v_pk_mul_f32 v[66:67], v[66:67], v[172:173] op_sel_hi:[1,0]
	v_mfma_f32_32x32x16_bf16 v[84:99], v[160:163], v[0:3], v[84:99]
	v_mul_f32_e64 v64, v64, v172
	v_mul_f32_e64 v65, v65, v172
	v_mul_f32_e64 v62, v62, v172
	v_mul_f32_e64 v63, v63, v172
	v_mul_f32_e64 v60, v60, v172
	v_mul_f32_e64 v61, v61, v172
	v_pk_mul_f32 v[58:59], v[58:59], v[172:173] op_sel_hi:[1,0]
	v_pk_mul_f32 v[56:57], v[56:57], v[172:173] op_sel_hi:[1,0]
	v_pk_mul_f32 v[54:55], v[54:55], v[172:173] op_sel_hi:[1,0]
	v_pk_mul_f32 v[52:53], v[52:53], v[172:173] op_sel_hi:[1,0]
	v_pk_mul_f32 v[50:51], v[50:51], v[172:173] op_sel_hi:[1,0]
	v_pk_mul_f32 v[48:49], v[48:49], v[172:173] op_sel_hi:[1,0]
	v_pk_mul_f32 v[46:47], v[46:47], v[172:173] op_sel_hi:[1,0]
	v_pk_mul_f32 v[44:45], v[44:45], v[172:173] op_sel_hi:[1,0]
	v_pk_mul_f32 v[42:43], v[42:43], v[172:173] op_sel_hi:[1,0]
	v_pk_mul_f32 v[40:41], v[40:41], v[172:173] op_sel_hi:[1,0]
	v_pk_mul_f32 v[38:39], v[38:39], v[172:173] op_sel_hi:[1,0]
	v_pk_mul_f32 v[36:37], v[36:37], v[172:173] op_sel_hi:[1,0]
	s_branch .LBB0_2859
